# NSA edge tiles: masked interior-style code specialised per case (fully masked half not computed, fully valid half not masked)
# speedup vs baseline: 1.0071x; 1.0071x over previous
.LBB0_289:
	s_add_i32 s4, s15, 1
	s_cmp_gt_i32 s4, s8
	s_cbranch_scc1 .Lnsw_ehe
	v_and_b32_e32 v173, 31, v133
	v_bfe_u32 v213, v133, 5, 1
	v_lshlrev_b32_e32 v213, 3, v213
	v_sub_u32_e32 v173, v173, v213
	s_sub_i32 s4, s8, s15
	v_add_u32_e32 v173, s4, v173
	v_add_u32_e32 v213, 0xffffffe0, v173
	v_mov_b32_e32 v174, 0xff800000
	v_mad_u32_u24 v0, v217, s37, v3
	v_lshl_add_u32 v215, v156, 1, v3
	ds_read_b128 v[220:223], v0
	ds_read_b128 v[236:239], v0 offset:4608
	ds_read_b128 v[224:227], v0 offset:32
	ds_read_b128 v[240:243], v0 offset:4640
	ds_read_b128 v[228:231], v0 offset:64
	ds_read_b128 v[244:247], v0 offset:4672
	ds_read_b128 v[232:235], v0 offset:96
	ds_read_b128 v[248:251], v0 offset:4704
	ds_read_b128 v[64:67], v215 offset:9216
	ds_read_b128 v[68:71], v215 offset:13824
	ds_read_b128 v[72:75], v215 offset:9248
	ds_read_b128 v[76:79], v215 offset:13856
	s_waitcnt lgkmcnt(11)
	v_mfma_f32_32x32x16_bf16 v[80:95], v[220:223], v[96:99], 0
	s_waitcnt lgkmcnt(10)
	v_mfma_f32_32x32x16_bf16 v[48:63], v[236:239], v[96:99], 0
	s_waitcnt lgkmcnt(9)
	v_mfma_f32_32x32x16_bf16 v[80:95], v[224:227], v[100:103], v[80:95]
	s_waitcnt lgkmcnt(8)
	v_mfma_f32_32x32x16_bf16 v[48:63], v[240:243], v[100:103], v[48:63]
	s_waitcnt lgkmcnt(7)
	v_mfma_f32_32x32x16_bf16 v[80:95], v[228:231], v[104:107], v[80:95]
	s_waitcnt lgkmcnt(6)
	v_mfma_f32_32x32x16_bf16 v[48:63], v[244:247], v[104:107], v[48:63]
	s_waitcnt lgkmcnt(5)
	v_mfma_f32_32x32x16_bf16 v[80:95], v[232:235], v[108:111], v[80:95]
	s_waitcnt lgkmcnt(4)
	v_mfma_f32_32x32x16_bf16 v[48:63], v[248:251], v[108:111], v[48:63]
	ds_read_b128 v[220:223], v215 offset:9280
	ds_read_b128 v[224:227], v215 offset:13888
	ds_read_b128 v[228:231], v215 offset:9312
	ds_read_b128 v[232:235], v215 offset:13920
	s_nop 7
	s_nop 3
	v_cmp_le_i32_e64 vcc, 0, v213
	v_cmp_le_i32_e64 s[4:5], 1, v213
	v_cmp_le_i32_e64 s[6:7], 2, v213
	v_cndmask_b32_e32 v48, v174, v48, vcc
	v_cmp_le_i32_e64 vcc, 3, v213
	v_cndmask_b32_e64 v49, v174, v49, s[4:5]
	v_cmp_le_i32_e64 s[4:5], 4, v213
	v_cndmask_b32_e64 v50, v174, v50, s[6:7]
	v_cmp_le_i32_e64 s[6:7], 5, v213
	v_cndmask_b32_e32 v51, v174, v51, vcc
	v_cmp_le_i32_e64 vcc, 6, v213
	v_cndmask_b32_e64 v52, v174, v52, s[4:5]
	v_cmp_le_i32_e64 s[4:5], 7, v213
	v_cndmask_b32_e64 v53, v174, v53, s[6:7]
	v_cmp_le_i32_e64 s[6:7], 16, v213
	v_cndmask_b32_e32 v54, v174, v54, vcc
	v_cmp_le_i32_e64 vcc, 17, v213
	v_cndmask_b32_e64 v55, v174, v55, s[4:5]
	v_cmp_le_i32_e64 s[4:5], 18, v213
	v_cndmask_b32_e64 v56, v174, v56, s[6:7]
	v_cmp_le_i32_e64 s[6:7], 19, v213
	v_cndmask_b32_e32 v57, v174, v57, vcc
	v_cmp_le_i32_e64 vcc, 20, v213
	v_cndmask_b32_e64 v58, v174, v58, s[4:5]
	v_cmp_le_i32_e64 s[4:5], 21, v213
	v_cndmask_b32_e64 v59, v174, v59, s[6:7]
	v_cmp_le_i32_e64 s[6:7], 22, v213
	v_cndmask_b32_e32 v60, v174, v60, vcc
	v_cmp_le_i32_e64 vcc, 23, v213
	v_cndmask_b32_e64 v61, v174, v61, s[4:5]
	s_nop 0
	v_cndmask_b32_e64 v62, v174, v62, s[6:7]
	s_nop 0
	v_cndmask_b32_e32 v63, v174, v63, vcc
	s_nop 0
	v_max3_f32 v0, v80, v81, v82
	v_max3_f32 v2, v88, v89, v90
	v_max3_f32 v0, v0, v83, v84
	v_max3_f32 v2, v2, v91, v92
	v_max3_f32 v0, v0, v85, v86
	v_max3_f32 v2, v2, v93, v94
	v_max3_f32 v0, v0, v87, v95
	v_max_f32_e32 v0, v0, v2
	v_max3_f32 v175, v48, v49, v50
	v_max3_f32 v214, v56, v57, v58
	v_max3_f32 v175, v175, v51, v52
	v_max3_f32 v214, v214, v59, v60
	v_max3_f32 v175, v175, v53, v54
	v_max3_f32 v214, v214, v61, v62
	v_max3_f32 v175, v175, v55, v63
	v_max_f32_e32 v175, v175, v214
	v_cmp_gt_f32_e32 vcc, v0, v219
	s_andn2_b64 vcc, vcc, s[38:39]
	s_cmp_eq_u64 vcc, 0
	s_cbranch_scc1 .Lnsweho_keep0
	v_cndmask_b32_e64 v0, v0, v202, s[38:39]
	s_nop 0
	ds_bpermute_b32 v2, v119, v0
	s_waitcnt lgkmcnt(0)
	v_max_f32_e32 v0, v0, v2
	v_max_f32_e32 v173, v167, v0
	v_sub_f32_e32 v0, v167, v173
	v_exp_f32_e32 v0, v0
	v_mov_b32_e32 v167, v173
	v_add_f32_e32 v219, 0x41200000, v173
	v_mul_f32_e32 v169, v169, v0
	v_pk_mul_f32 v[46:47], v[46:47], v[0:1] op_sel_hi:[1,0]
	v_pk_mul_f32 v[44:45], v[44:45], v[0:1] op_sel_hi:[1,0]
	v_pk_mul_f32 v[42:43], v[42:43], v[0:1] op_sel_hi:[1,0]
	v_pk_mul_f32 v[40:41], v[40:41], v[0:1] op_sel_hi:[1,0]
	v_pk_mul_f32 v[38:39], v[38:39], v[0:1] op_sel_hi:[1,0]
	v_pk_mul_f32 v[36:37], v[36:37], v[0:1] op_sel_hi:[1,0]
	v_pk_mul_f32 v[34:35], v[34:35], v[0:1] op_sel_hi:[1,0]
	v_pk_mul_f32 v[32:33], v[32:33], v[0:1] op_sel_hi:[1,0]
	v_pk_mul_f32 v[30:31], v[30:31], v[0:1] op_sel_hi:[1,0]
	v_pk_mul_f32 v[28:29], v[28:29], v[0:1] op_sel_hi:[1,0]
	v_pk_mul_f32 v[26:27], v[26:27], v[0:1] op_sel_hi:[1,0]
	v_pk_mul_f32 v[24:25], v[24:25], v[0:1] op_sel_hi:[1,0]
	v_pk_mul_f32 v[22:23], v[22:23], v[0:1] op_sel_hi:[1,0]
	v_pk_mul_f32 v[20:21], v[20:21], v[0:1] op_sel_hi:[1,0]
	v_pk_mul_f32 v[18:19], v[18:19], v[0:1] op_sel_hi:[1,0]
	v_pk_mul_f32 v[16:17], v[16:17], v[0:1] op_sel_hi:[1,0]

.Lnsw_ehe:
	v_and_b32_e32 v173, 31, v133
	v_bfe_u32 v213, v133, 5, 1
	v_lshlrev_b32_e32 v213, 3, v213
	v_sub_u32_e32 v173, v173, v213
	s_sub_i32 s4, s8, s15
	v_add_u32_e32 v173, s4, v173
	v_add_u32_e32 v213, 0xffffffe0, v173
	v_mov_b32_e32 v174, 0xff800000
	v_mad_u32_u24 v0, v217, s37, v3
	v_lshl_add_u32 v215, v156, 1, v3
	ds_read_b128 v[220:223], v0
	ds_read_b128 v[224:227], v0 offset:32
	ds_read_b128 v[228:231], v0 offset:64
	ds_read_b128 v[232:235], v0 offset:96
	ds_read_b128 v[64:67], v215 offset:9216
	ds_read_b128 v[68:71], v215 offset:13824
	ds_read_b128 v[72:75], v215 offset:9248
	ds_read_b128 v[76:79], v215 offset:13856
	s_waitcnt lgkmcnt(7)
	v_mfma_f32_32x32x16_bf16 v[80:95], v[220:223], v[96:99], 0
	s_waitcnt lgkmcnt(6)
	v_mfma_f32_32x32x16_bf16 v[80:95], v[224:227], v[100:103], v[80:95]
	s_waitcnt lgkmcnt(5)
	v_mfma_f32_32x32x16_bf16 v[80:95], v[228:231], v[104:107], v[80:95]
	s_waitcnt lgkmcnt(4)
	v_mfma_f32_32x32x16_bf16 v[80:95], v[232:235], v[108:111], v[80:95]
	s_nop 7
	s_nop 3
	v_cmp_le_i32_e64 vcc, 0, v173
	v_cmp_le_i32_e64 s[4:5], 1, v173
	v_cmp_le_i32_e64 s[6:7], 2, v173
	v_cndmask_b32_e32 v80, v174, v80, vcc
	v_cmp_le_i32_e64 vcc, 3, v173
	v_cndmask_b32_e64 v81, v174, v81, s[4:5]
	v_cmp_le_i32_e64 s[4:5], 4, v173
	v_cndmask_b32_e64 v82, v174, v82, s[6:7]
	v_cmp_le_i32_e64 s[6:7], 5, v173
	v_cndmask_b32_e32 v83, v174, v83, vcc
	v_cmp_le_i32_e64 vcc, 6, v173
	v_cndmask_b32_e64 v84, v174, v84, s[4:5]
	v_cmp_le_i32_e64 s[4:5], 7, v173
	v_cndmask_b32_e64 v85, v174, v85, s[6:7]
	v_cmp_le_i32_e64 s[6:7], 16, v173
	v_cndmask_b32_e32 v86, v174, v86, vcc
	v_cmp_le_i32_e64 vcc, 17, v173
	v_cndmask_b32_e64 v87, v174, v87, s[4:5]
	v_cmp_le_i32_e64 s[4:5], 18, v173
	v_cndmask_b32_e64 v88, v174, v88, s[6:7]
	v_cmp_le_i32_e64 s[6:7], 19, v173
	v_cndmask_b32_e32 v89, v174, v89, vcc
	v_cmp_le_i32_e64 vcc, 20, v173
	v_cndmask_b32_e64 v90, v174, v90, s[4:5]
	v_cmp_le_i32_e64 s[4:5], 21, v173
	v_cndmask_b32_e64 v91, v174, v91, s[6:7]
	v_cmp_le_i32_e64 s[6:7], 22, v173
	v_cndmask_b32_e32 v92, v174, v92, vcc
	v_cmp_le_i32_e64 vcc, 23, v173
	v_cndmask_b32_e64 v93, v174, v93, s[4:5]
	s_nop 0
	v_cndmask_b32_e64 v94, v174, v94, s[6:7]
	s_nop 0
	v_cndmask_b32_e32 v95, v174, v95, vcc
	s_nop 0
	v_max3_f32 v0, v80, v81, v82
	v_max3_f32 v2, v88, v89, v90
	v_max3_f32 v0, v0, v83, v84
	v_max3_f32 v2, v2, v91, v92
	v_max3_f32 v0, v0, v85, v86
	v_max3_f32 v2, v2, v93, v94
	v_max3_f32 v0, v0, v87, v95
	v_max_f32_e32 v0, v0, v2
	v_cmp_gt_f32_e32 vcc, v0, v219
	s_andn2_b64 vcc, vcc, s[38:39]
	s_cmp_eq_u64 vcc, 0
	s_cbranch_scc1 .Lnswehe_keep0
	v_cndmask_b32_e64 v0, v0, v202, s[38:39]
	s_nop 0
	ds_bpermute_b32 v2, v119, v0
	s_waitcnt lgkmcnt(0)
	v_max_f32_e32 v0, v0, v2
	v_max_f32_e32 v173, v167, v0
	v_sub_f32_e32 v0, v167, v173
	v_exp_f32_e32 v0, v0
	v_mov_b32_e32 v167, v173
	v_add_f32_e32 v219, 0x41200000, v173
	v_mul_f32_e32 v169, v169, v0
	v_pk_mul_f32 v[46:47], v[46:47], v[0:1] op_sel_hi:[1,0]
	v_pk_mul_f32 v[44:45], v[44:45], v[0:1] op_sel_hi:[1,0]
	v_pk_mul_f32 v[42:43], v[42:43], v[0:1] op_sel_hi:[1,0]
	v_pk_mul_f32 v[40:41], v[40:41], v[0:1] op_sel_hi:[1,0]
	v_pk_mul_f32 v[38:39], v[38:39], v[0:1] op_sel_hi:[1,0]
	v_pk_mul_f32 v[36:37], v[36:37], v[0:1] op_sel_hi:[1,0]
	v_pk_mul_f32 v[34:35], v[34:35], v[0:1] op_sel_hi:[1,0]
	v_pk_mul_f32 v[32:33], v[32:33], v[0:1] op_sel_hi:[1,0]
	v_pk_mul_f32 v[30:31], v[30:31], v[0:1] op_sel_hi:[1,0]
	v_pk_mul_f32 v[28:29], v[28:29], v[0:1] op_sel_hi:[1,0]
	v_pk_mul_f32 v[26:27], v[26:27], v[0:1] op_sel_hi:[1,0]
	v_pk_mul_f32 v[24:25], v[24:25], v[0:1] op_sel_hi:[1,0]
	v_pk_mul_f32 v[22:23], v[22:23], v[0:1] op_sel_hi:[1,0]
	v_pk_mul_f32 v[20:21], v[20:21], v[0:1] op_sel_hi:[1,0]
	v_pk_mul_f32 v[18:19], v[18:19], v[0:1] op_sel_hi:[1,0]
	v_pk_mul_f32 v[16:17], v[16:17], v[0:1] op_sel_hi:[1,0]
.Lnswehe_keep0:
	v_cndmask_b32_e64 v174, v167, v206, s[38:39]
	v_sub_f32_e32 v80, v80, v174
	v_exp_f32_e32 v80, v80
	v_sub_f32_e32 v81, v81, v174
	v_exp_f32_e32 v81, v81
	v_sub_f32_e32 v82, v82, v174
	v_exp_f32_e32 v82, v82
	v_add_f32_e32 v213, v81, v80
	v_sub_f32_e32 v83, v83, v174
	v_exp_f32_e32 v83, v83
	v_add_f32_e32 v213, v82, v213
	v_cvt_pk_bf16_f32 v176, v80, v81
	v_sub_f32_e32 v84, v84, v174
	v_exp_f32_e32 v84, v84
	v_add_f32_e32 v213, v83, v213
	v_sub_f32_e32 v85, v85, v174
	v_exp_f32_e32 v85, v85
	v_add_f32_e32 v213, v84, v213
	v_cvt_pk_bf16_f32 v177, v82, v83
	v_sub_f32_e32 v86, v86, v174
	v_exp_f32_e32 v86, v86
	v_add_f32_e32 v213, v85, v213
	v_sub_f32_e32 v87, v87, v174
	v_exp_f32_e32 v87, v87
	v_add_f32_e32 v213, v86, v213
	v_cvt_pk_bf16_f32 v178, v84, v85
	v_sub_f32_e32 v88, v88, v174
	v_exp_f32_e32 v88, v88
	v_add_f32_e32 v213, v87, v213
	v_sub_f32_e32 v89, v89, v174
	v_exp_f32_e32 v89, v89
	v_add_f32_e32 v213, v88, v213
	v_cvt_pk_bf16_f32 v179, v86, v87
	v_sub_f32_e32 v90, v90, v174
	v_exp_f32_e32 v90, v90
	v_add_f32_e32 v213, v89, v213
	s_waitcnt lgkmcnt(3)
	v_mfma_f32_32x32x16_bf16 v[32:47], v[64:67], v[176:179], v[32:47]
	s_waitcnt lgkmcnt(2)
	v_mfma_f32_32x32x16_bf16 v[16:31], v[68:71], v[176:179], v[16:31]
	v_sub_f32_e32 v91, v91, v174
	v_exp_f32_e32 v91, v91
	v_add_f32_e32 v213, v90, v213
	v_cvt_pk_bf16_f32 v180, v88, v89
	v_sub_f32_e32 v92, v92, v174
	v_exp_f32_e32 v92, v92
	v_add_f32_e32 v213, v91, v213
	v_sub_f32_e32 v93, v93, v174
	v_exp_f32_e32 v93, v93
	v_add_f32_e32 v213, v92, v213
	v_cvt_pk_bf16_f32 v181, v90, v91
	v_sub_f32_e32 v94, v94, v174
	v_exp_f32_e32 v94, v94
	v_add_f32_e32 v213, v93, v213
	v_sub_f32_e32 v95, v95, v174
	v_exp_f32_e32 v95, v95
	v_add_f32_e32 v213, v94, v213
	v_cvt_pk_bf16_f32 v182, v92, v93
	v_add_f32_e32 v213, v95, v213
	v_cvt_pk_bf16_f32 v183, v94, v95
	v_add_f32_e32 v169, v169, v213
	s_nop 0
	s_waitcnt lgkmcnt(1)
	v_mfma_f32_32x32x16_bf16 v[32:47], v[72:75], v[180:183], v[32:47]
	s_waitcnt lgkmcnt(0)
	v_mfma_f32_32x32x16_bf16 v[16:31], v[76:79], v[180:183], v[16:31]

.LBB0_301:
	s_add_i32 s13, s12, 1
	s_min_i32 s4, s13, s10
	s_lshl_b32 s4, s4, 6
	s_ashr_i32 s5, s4, 31
	s_lshl_b64 s[6:7], s[4:5], 7
	s_lshl_b64 s[4:5], s[4:5], 1
	v_lshl_add_u64 v[14:15], v[190:191], 0, s[6:7]
	v_lshl_add_u64 v[10:11], v[164:165], 0, s[4:5]
	global_load_dwordx4 v[6:9], v[14:15], off offset:-2048
	s_nop 0
	global_load_dwordx4 v[2:5], v[14:15], off offset:2048
	v_lshl_add_u64 v[14:15], v[166:167], 0, s[4:5]
	global_load_dwordx4 v[10:13], v[10:11], off
	s_nop 0
	global_load_dwordx4 v[112:115], v[14:15], off
	s_sub_i32 s4, s12, s11
	s_lshl_b32 s6, s12, 6
	s_and_b32 s14, s4, 1
	s_or_b32 s4, s6, 63
	s_cmp_le_i32 s4, s8
	s_cselect_b64 s[4:5], -1, 0
	s_cmp_gt_i32 s6, s9
	s_mul_i32 s7, s14, 0x4800
	s_cselect_b64 s[16:17], -1, 0
	s_and_b64 s[16:17], s[4:5], s[16:17]
	v_or_b32_e32 v14, s7, v129
	s_mov_b64 s[4:5], -1
	s_and_b64 vcc, exec, s[16:17]
	v_add_u32_e32 v15, v14, v161
	s_cbranch_vccnz .LBB0_307
	s_cmp_le_i32 s6, s9
	s_cbranch_scc1 .Lnsw1_elo
	s_add_i32 s4, s6, 1
	s_cmp_gt_i32 s4, s8
	s_cbranch_scc1 .Lnsw1_ehe
	v_and_b32_e32 v173, 31, v133
	v_bfe_u32 v213, v133, 5, 1
	v_lshlrev_b32_e32 v213, 3, v213
	v_sub_u32_e32 v173, v173, v213
	s_sub_i32 s4, s8, s6
	v_add_u32_e32 v173, s4, v173
	v_add_u32_e32 v213, 0xffffffe0, v173
	v_mov_b32_e32 v174, 0xff800000
	v_mad_u32_u24 v0, v218, s37, v14
	v_lshl_add_u32 v215, v159, 1, v14
	ds_read_b128 v[220:223], v0
	ds_read_b128 v[236:239], v0 offset:4608
	ds_read_b128 v[224:227], v0 offset:32
	ds_read_b128 v[240:243], v0 offset:4640
	ds_read_b128 v[228:231], v0 offset:64
	ds_read_b128 v[244:247], v0 offset:4672
	ds_read_b128 v[232:235], v0 offset:96
	ds_read_b128 v[248:251], v0 offset:4704
	ds_read_b128 v[64:67], v215 offset:9216
	ds_read_b128 v[68:71], v215 offset:13824
	ds_read_b128 v[72:75], v215 offset:9248
	ds_read_b128 v[76:79], v215 offset:13856
	s_waitcnt lgkmcnt(11)
	v_mfma_f32_32x32x16_bf16 v[80:95], v[220:223], v[96:99], 0
	s_waitcnt lgkmcnt(10)
	v_mfma_f32_32x32x16_bf16 v[48:63], v[236:239], v[96:99], 0
	s_waitcnt lgkmcnt(9)
	v_mfma_f32_32x32x16_bf16 v[80:95], v[224:227], v[100:103], v[80:95]
	s_waitcnt lgkmcnt(8)
	v_mfma_f32_32x32x16_bf16 v[48:63], v[240:243], v[100:103], v[48:63]
	s_waitcnt lgkmcnt(7)
	v_mfma_f32_32x32x16_bf16 v[80:95], v[228:231], v[104:107], v[80:95]
	s_waitcnt lgkmcnt(6)
	v_mfma_f32_32x32x16_bf16 v[48:63], v[244:247], v[104:107], v[48:63]
	s_waitcnt lgkmcnt(5)
	v_mfma_f32_32x32x16_bf16 v[80:95], v[232:235], v[108:111], v[80:95]
	s_waitcnt lgkmcnt(4)
	v_mfma_f32_32x32x16_bf16 v[48:63], v[248:251], v[108:111], v[48:63]
	ds_read_b128 v[220:223], v215 offset:9280
	ds_read_b128 v[224:227], v215 offset:13888
	ds_read_b128 v[228:231], v215 offset:9312
	ds_read_b128 v[232:235], v215 offset:13920
	s_nop 7
	s_nop 3
	v_cmp_le_i32_e64 vcc, 0, v213
	v_cmp_le_i32_e64 s[4:5], 1, v213
	v_cmp_le_i32_e64 s[6:7], 2, v213
	v_cndmask_b32_e32 v48, v174, v48, vcc
	v_cmp_le_i32_e64 vcc, 3, v213
	v_cndmask_b32_e64 v49, v174, v49, s[4:5]
	v_cmp_le_i32_e64 s[4:5], 4, v213
	v_cndmask_b32_e64 v50, v174, v50, s[6:7]
	v_cmp_le_i32_e64 s[6:7], 5, v213
	v_cndmask_b32_e32 v51, v174, v51, vcc
	v_cmp_le_i32_e64 vcc, 6, v213
	v_cndmask_b32_e64 v52, v174, v52, s[4:5]
	v_cmp_le_i32_e64 s[4:5], 7, v213
	v_cndmask_b32_e64 v53, v174, v53, s[6:7]
	v_cmp_le_i32_e64 s[6:7], 16, v213
	v_cndmask_b32_e32 v54, v174, v54, vcc
	v_cmp_le_i32_e64 vcc, 17, v213
	v_cndmask_b32_e64 v55, v174, v55, s[4:5]
	v_cmp_le_i32_e64 s[4:5], 18, v213
	v_cndmask_b32_e64 v56, v174, v56, s[6:7]
	v_cmp_le_i32_e64 s[6:7], 19, v213
	v_cndmask_b32_e32 v57, v174, v57, vcc
	v_cmp_le_i32_e64 vcc, 20, v213
	v_cndmask_b32_e64 v58, v174, v58, s[4:5]
	v_cmp_le_i32_e64 s[4:5], 21, v213
	v_cndmask_b32_e64 v59, v174, v59, s[6:7]
	v_cmp_le_i32_e64 s[6:7], 22, v213
	v_cndmask_b32_e32 v60, v174, v60, vcc
	v_cmp_le_i32_e64 vcc, 23, v213
	v_cndmask_b32_e64 v61, v174, v61, s[4:5]
	s_nop 0
	v_cndmask_b32_e64 v62, v174, v62, s[6:7]
	s_nop 0
	v_cndmask_b32_e32 v63, v174, v63, vcc
	s_nop 0
	v_max3_f32 v0, v80, v81, v82
	v_max3_f32 v216, v88, v89, v90
	v_max3_f32 v0, v0, v83, v84
	v_max3_f32 v216, v216, v91, v92
	v_max3_f32 v0, v0, v85, v86
	v_max3_f32 v216, v216, v93, v94
	v_max3_f32 v0, v0, v87, v95
	v_max_f32_e32 v0, v0, v216
	v_max3_f32 v175, v48, v49, v50
	v_max3_f32 v214, v56, v57, v58
	v_max3_f32 v175, v175, v51, v52
	v_max3_f32 v214, v214, v59, v60
	v_max3_f32 v175, v175, v53, v54
	v_max3_f32 v214, v214, v61, v62
	v_max3_f32 v175, v175, v55, v63
	v_max_f32_e32 v175, v175, v214
	v_cmp_gt_f32_e32 vcc, v0, v219
	s_cmp_eq_u64 vcc, 0
	s_cbranch_scc1 .Lnsw1eho_keep0
	s_nop 0
	ds_bpermute_b32 v216, v119, v0
	s_waitcnt lgkmcnt(0)
	v_max_f32_e32 v0, v0, v216
	v_max_f32_e32 v173, v168, v0
	v_sub_f32_e32 v0, v168, v173
	v_exp_f32_e32 v0, v0
	v_mov_b32_e32 v168, v173
	v_add_f32_e32 v219, 0x41200000, v173
	v_mul_f32_e32 v169, v169, v0
	v_pk_mul_f32 v[46:47], v[46:47], v[0:1] op_sel_hi:[1,0]
	v_pk_mul_f32 v[44:45], v[44:45], v[0:1] op_sel_hi:[1,0]
	v_pk_mul_f32 v[42:43], v[42:43], v[0:1] op_sel_hi:[1,0]
	v_pk_mul_f32 v[40:41], v[40:41], v[0:1] op_sel_hi:[1,0]
	v_pk_mul_f32 v[38:39], v[38:39], v[0:1] op_sel_hi:[1,0]
	v_pk_mul_f32 v[36:37], v[36:37], v[0:1] op_sel_hi:[1,0]
	v_pk_mul_f32 v[34:35], v[34:35], v[0:1] op_sel_hi:[1,0]
	v_pk_mul_f32 v[32:33], v[32:33], v[0:1] op_sel_hi:[1,0]
	v_pk_mul_f32 v[30:31], v[30:31], v[0:1] op_sel_hi:[1,0]
	v_pk_mul_f32 v[28:29], v[28:29], v[0:1] op_sel_hi:[1,0]
	v_pk_mul_f32 v[26:27], v[26:27], v[0:1] op_sel_hi:[1,0]
	v_pk_mul_f32 v[24:25], v[24:25], v[0:1] op_sel_hi:[1,0]
	v_pk_mul_f32 v[22:23], v[22:23], v[0:1] op_sel_hi:[1,0]
	v_pk_mul_f32 v[20:21], v[20:21], v[0:1] op_sel_hi:[1,0]
	v_pk_mul_f32 v[18:19], v[18:19], v[0:1] op_sel_hi:[1,0]
	v_pk_mul_f32 v[16:17], v[16:17], v[0:1] op_sel_hi:[1,0]

.Lnsw1_ehe:
	v_and_b32_e32 v173, 31, v133
	v_bfe_u32 v213, v133, 5, 1
	v_lshlrev_b32_e32 v213, 3, v213
	v_sub_u32_e32 v173, v173, v213
	s_sub_i32 s4, s8, s6
	v_add_u32_e32 v173, s4, v173
	v_add_u32_e32 v213, 0xffffffe0, v173
	v_mov_b32_e32 v174, 0xff800000
	v_mad_u32_u24 v0, v218, s37, v14
	v_lshl_add_u32 v215, v159, 1, v14
	ds_read_b128 v[220:223], v0
	ds_read_b128 v[224:227], v0 offset:32
	ds_read_b128 v[228:231], v0 offset:64
	ds_read_b128 v[232:235], v0 offset:96
	ds_read_b128 v[64:67], v215 offset:9216
	ds_read_b128 v[68:71], v215 offset:13824
	ds_read_b128 v[72:75], v215 offset:9248
	ds_read_b128 v[76:79], v215 offset:13856
	s_waitcnt lgkmcnt(7)
	v_mfma_f32_32x32x16_bf16 v[80:95], v[220:223], v[96:99], 0
	s_waitcnt lgkmcnt(6)
	v_mfma_f32_32x32x16_bf16 v[80:95], v[224:227], v[100:103], v[80:95]
	s_waitcnt lgkmcnt(5)
	v_mfma_f32_32x32x16_bf16 v[80:95], v[228:231], v[104:107], v[80:95]
	s_waitcnt lgkmcnt(4)
	v_mfma_f32_32x32x16_bf16 v[80:95], v[232:235], v[108:111], v[80:95]
	s_nop 7
	s_nop 3
	v_cmp_le_i32_e64 vcc, 0, v173
	v_cmp_le_i32_e64 s[4:5], 1, v173
	v_cmp_le_i32_e64 s[6:7], 2, v173
	v_cndmask_b32_e32 v80, v174, v80, vcc
	v_cmp_le_i32_e64 vcc, 3, v173
	v_cndmask_b32_e64 v81, v174, v81, s[4:5]
	v_cmp_le_i32_e64 s[4:5], 4, v173
	v_cndmask_b32_e64 v82, v174, v82, s[6:7]
	v_cmp_le_i32_e64 s[6:7], 5, v173
	v_cndmask_b32_e32 v83, v174, v83, vcc
	v_cmp_le_i32_e64 vcc, 6, v173
	v_cndmask_b32_e64 v84, v174, v84, s[4:5]
	v_cmp_le_i32_e64 s[4:5], 7, v173
	v_cndmask_b32_e64 v85, v174, v85, s[6:7]
	v_cmp_le_i32_e64 s[6:7], 16, v173
	v_cndmask_b32_e32 v86, v174, v86, vcc
	v_cmp_le_i32_e64 vcc, 17, v173
	v_cndmask_b32_e64 v87, v174, v87, s[4:5]
	v_cmp_le_i32_e64 s[4:5], 18, v173
	v_cndmask_b32_e64 v88, v174, v88, s[6:7]
	v_cmp_le_i32_e64 s[6:7], 19, v173
	v_cndmask_b32_e32 v89, v174, v89, vcc
	v_cmp_le_i32_e64 vcc, 20, v173
	v_cndmask_b32_e64 v90, v174, v90, s[4:5]
	v_cmp_le_i32_e64 s[4:5], 21, v173
	v_cndmask_b32_e64 v91, v174, v91, s[6:7]
	v_cmp_le_i32_e64 s[6:7], 22, v173
	v_cndmask_b32_e32 v92, v174, v92, vcc
	v_cmp_le_i32_e64 vcc, 23, v173
	v_cndmask_b32_e64 v93, v174, v93, s[4:5]
	s_nop 0
	v_cndmask_b32_e64 v94, v174, v94, s[6:7]
	s_nop 0
	v_cndmask_b32_e32 v95, v174, v95, vcc
	s_nop 0
	v_max3_f32 v0, v80, v81, v82
	v_max3_f32 v216, v88, v89, v90
	v_max3_f32 v0, v0, v83, v84
	v_max3_f32 v216, v216, v91, v92
	v_max3_f32 v0, v0, v85, v86
	v_max3_f32 v216, v216, v93, v94
	v_max3_f32 v0, v0, v87, v95
	v_max_f32_e32 v0, v0, v216
	v_cmp_gt_f32_e32 vcc, v0, v219
	s_cmp_eq_u64 vcc, 0
	s_cbranch_scc1 .Lnsw1ehe_keep0
	s_nop 0
	ds_bpermute_b32 v216, v119, v0
	s_waitcnt lgkmcnt(0)
	v_max_f32_e32 v0, v0, v216
	v_max_f32_e32 v173, v168, v0
	v_sub_f32_e32 v0, v168, v173
	v_exp_f32_e32 v0, v0
	v_mov_b32_e32 v168, v173
	v_add_f32_e32 v219, 0x41200000, v173
	v_mul_f32_e32 v169, v169, v0
	v_pk_mul_f32 v[46:47], v[46:47], v[0:1] op_sel_hi:[1,0]
	v_pk_mul_f32 v[44:45], v[44:45], v[0:1] op_sel_hi:[1,0]
	v_pk_mul_f32 v[42:43], v[42:43], v[0:1] op_sel_hi:[1,0]
	v_pk_mul_f32 v[40:41], v[40:41], v[0:1] op_sel_hi:[1,0]
	v_pk_mul_f32 v[38:39], v[38:39], v[0:1] op_sel_hi:[1,0]
	v_pk_mul_f32 v[36:37], v[36:37], v[0:1] op_sel_hi:[1,0]
	v_pk_mul_f32 v[34:35], v[34:35], v[0:1] op_sel_hi:[1,0]
	v_pk_mul_f32 v[32:33], v[32:33], v[0:1] op_sel_hi:[1,0]
	v_pk_mul_f32 v[30:31], v[30:31], v[0:1] op_sel_hi:[1,0]
	v_pk_mul_f32 v[28:29], v[28:29], v[0:1] op_sel_hi:[1,0]
	v_pk_mul_f32 v[26:27], v[26:27], v[0:1] op_sel_hi:[1,0]
	v_pk_mul_f32 v[24:25], v[24:25], v[0:1] op_sel_hi:[1,0]
	v_pk_mul_f32 v[22:23], v[22:23], v[0:1] op_sel_hi:[1,0]
	v_pk_mul_f32 v[20:21], v[20:21], v[0:1] op_sel_hi:[1,0]
	v_pk_mul_f32 v[18:19], v[18:19], v[0:1] op_sel_hi:[1,0]
	v_pk_mul_f32 v[16:17], v[16:17], v[0:1] op_sel_hi:[1,0]
.Lnsw1ehe_keep0:
	v_sub_f32_e32 v80, v80, v168
	v_exp_f32_e32 v80, v80
	v_sub_f32_e32 v81, v81, v168
	v_exp_f32_e32 v81, v81
	v_sub_f32_e32 v82, v82, v168
	v_exp_f32_e32 v82, v82
	v_add_f32_e32 v213, v81, v80
	v_sub_f32_e32 v83, v83, v168
	v_exp_f32_e32 v83, v83
	v_add_f32_e32 v213, v82, v213
	v_cvt_pk_bf16_f32 v176, v80, v81
	v_sub_f32_e32 v84, v84, v168
	v_exp_f32_e32 v84, v84
	v_add_f32_e32 v213, v83, v213
	v_sub_f32_e32 v85, v85, v168
	v_exp_f32_e32 v85, v85
	v_add_f32_e32 v213, v84, v213
	v_cvt_pk_bf16_f32 v177, v82, v83
	v_sub_f32_e32 v86, v86, v168
	v_exp_f32_e32 v86, v86
	v_add_f32_e32 v213, v85, v213
	v_sub_f32_e32 v87, v87, v168
	v_exp_f32_e32 v87, v87
	v_add_f32_e32 v213, v86, v213
	v_cvt_pk_bf16_f32 v178, v84, v85
	v_sub_f32_e32 v88, v88, v168
	v_exp_f32_e32 v88, v88
	v_add_f32_e32 v213, v87, v213
	v_sub_f32_e32 v89, v89, v168
	v_exp_f32_e32 v89, v89
	v_add_f32_e32 v213, v88, v213
	v_cvt_pk_bf16_f32 v179, v86, v87
	v_sub_f32_e32 v90, v90, v168
	v_exp_f32_e32 v90, v90
	v_add_f32_e32 v213, v89, v213
	s_waitcnt lgkmcnt(3)
	v_mfma_f32_32x32x16_bf16 v[32:47], v[64:67], v[176:179], v[32:47]
	s_waitcnt lgkmcnt(2)
	v_mfma_f32_32x32x16_bf16 v[16:31], v[68:71], v[176:179], v[16:31]
	v_sub_f32_e32 v91, v91, v168
	v_exp_f32_e32 v91, v91
	v_add_f32_e32 v213, v90, v213
	v_cvt_pk_bf16_f32 v180, v88, v89
	v_sub_f32_e32 v92, v92, v168
	v_exp_f32_e32 v92, v92
	v_add_f32_e32 v213, v91, v213
	v_sub_f32_e32 v93, v93, v168
	v_exp_f32_e32 v93, v93
	v_add_f32_e32 v213, v92, v213
	v_cvt_pk_bf16_f32 v181, v90, v91
	v_sub_f32_e32 v94, v94, v168
	v_exp_f32_e32 v94, v94
	v_add_f32_e32 v213, v93, v213
	v_sub_f32_e32 v95, v95, v168
	v_exp_f32_e32 v95, v95
	v_add_f32_e32 v213, v94, v213
	v_cvt_pk_bf16_f32 v182, v92, v93
	v_add_f32_e32 v213, v95, v213
	v_cvt_pk_bf16_f32 v183, v94, v95
	v_add_f32_e32 v169, v169, v213
	s_nop 0
	s_waitcnt lgkmcnt(1)
	v_mfma_f32_32x32x16_bf16 v[32:47], v[72:75], v[180:183], v[32:47]
	s_waitcnt lgkmcnt(0)
	v_mfma_f32_32x32x16_bf16 v[16:31], v[76:79], v[180:183], v[16:31]
	s_branch .LBB0_314
.Lnsw1_elo:
	s_add_i32 s4, s6, 62
	s_cmp_le_i32 s4, s9
	s_cbranch_scc1 .Lnsw1_elo1
	v_and_b32_e32 v173, 31, v133
	v_bfe_u32 v213, v133, 5, 1
	v_lshlrev_b32_e32 v213, 3, v213
	v_sub_u32_e32 v173, v173, v213
	s_sub_i32 s4, s8, s6
	s_addk_i32 s4, 0xfe00
	v_add_u32_e32 v173, s4, v173
	v_add_u32_e32 v213, 0xffffffe0, v173
	v_mov_b32_e32 v174, 0xff800000
	v_mad_u32_u24 v0, v218, s37, v14
	v_lshl_add_u32 v215, v159, 1, v14
	ds_read_b128 v[220:223], v0
	ds_read_b128 v[236:239], v0 offset:4608
	ds_read_b128 v[224:227], v0 offset:32
	ds_read_b128 v[240:243], v0 offset:4640
	ds_read_b128 v[228:231], v0 offset:64
	ds_read_b128 v[244:247], v0 offset:4672
	ds_read_b128 v[232:235], v0 offset:96
	ds_read_b128 v[248:251], v0 offset:4704
	ds_read_b128 v[64:67], v215 offset:9216
	ds_read_b128 v[68:71], v215 offset:13824
	ds_read_b128 v[72:75], v215 offset:9248
	ds_read_b128 v[76:79], v215 offset:13856
	s_waitcnt lgkmcnt(11)
	v_mfma_f32_32x32x16_bf16 v[80:95], v[220:223], v[96:99], 0
	s_waitcnt lgkmcnt(10)
	v_mfma_f32_32x32x16_bf16 v[48:63], v[236:239], v[96:99], 0
	s_waitcnt lgkmcnt(9)
	v_mfma_f32_32x32x16_bf16 v[80:95], v[224:227], v[100:103], v[80:95]
	s_waitcnt lgkmcnt(8)
	v_mfma_f32_32x32x16_bf16 v[48:63], v[240:243], v[100:103], v[48:63]
	s_waitcnt lgkmcnt(7)
	v_mfma_f32_32x32x16_bf16 v[80:95], v[228:231], v[104:107], v[80:95]
	s_waitcnt lgkmcnt(6)
	v_mfma_f32_32x32x16_bf16 v[48:63], v[244:247], v[104:107], v[48:63]
	s_waitcnt lgkmcnt(5)
	v_mfma_f32_32x32x16_bf16 v[80:95], v[232:235], v[108:111], v[80:95]
	s_waitcnt lgkmcnt(4)
	v_mfma_f32_32x32x16_bf16 v[48:63], v[248:251], v[108:111], v[48:63]
	ds_read_b128 v[220:223], v215 offset:9280
	ds_read_b128 v[224:227], v215 offset:13888
	ds_read_b128 v[228:231], v215 offset:9312
	ds_read_b128 v[232:235], v215 offset:13920
	s_nop 7
	s_nop 3
	v_cmp_gt_i32_e64 vcc, 0, v173
	v_cmp_gt_i32_e64 s[4:5], 1, v173
	v_cmp_gt_i32_e64 s[6:7], 2, v173
	v_cndmask_b32_e32 v80, v174, v80, vcc
	v_cmp_gt_i32_e64 vcc, 3, v173
	v_cndmask_b32_e64 v81, v174, v81, s[4:5]
	v_cmp_gt_i32_e64 s[4:5], 4, v173
	v_cndmask_b32_e64 v82, v174, v82, s[6:7]
	v_cmp_gt_i32_e64 s[6:7], 5, v173
	v_cndmask_b32_e32 v83, v174, v83, vcc
	v_cmp_gt_i32_e64 vcc, 6, v173
	v_cndmask_b32_e64 v84, v174, v84, s[4:5]
	v_cmp_gt_i32_e64 s[4:5], 7, v173
	v_cndmask_b32_e64 v85, v174, v85, s[6:7]
	v_cmp_gt_i32_e64 s[6:7], 16, v173
	v_cndmask_b32_e32 v86, v174, v86, vcc
	v_cmp_gt_i32_e64 vcc, 17, v173
	v_cndmask_b32_e64 v87, v174, v87, s[4:5]
	v_cmp_gt_i32_e64 s[4:5], 18, v173
	v_cndmask_b32_e64 v88, v174, v88, s[6:7]
	v_cmp_gt_i32_e64 s[6:7], 19, v173
	v_cndmask_b32_e32 v89, v174, v89, vcc
	v_cmp_gt_i32_e64 vcc, 20, v173
	v_cndmask_b32_e64 v90, v174, v90, s[4:5]
	v_cmp_gt_i32_e64 s[4:5], 21, v173
	v_cndmask_b32_e64 v91, v174, v91, s[6:7]
	v_cmp_gt_i32_e64 s[6:7], 22, v173
	v_cndmask_b32_e32 v92, v174, v92, vcc
	v_cmp_gt_i32_e64 vcc, 23, v173
	v_cndmask_b32_e64 v93, v174, v93, s[4:5]
	s_nop 0
	v_cndmask_b32_e64 v94, v174, v94, s[6:7]
	s_nop 0
	v_cndmask_b32_e32 v95, v174, v95, vcc
	s_nop 0
	v_max3_f32 v0, v80, v81, v82
	v_max3_f32 v216, v88, v89, v90
	v_max3_f32 v0, v0, v83, v84
	v_max3_f32 v216, v216, v91, v92
	v_max3_f32 v0, v0, v85, v86
	v_max3_f32 v216, v216, v93, v94
	v_max3_f32 v0, v0, v87, v95
	v_max_f32_e32 v0, v0, v216
	v_max3_f32 v175, v48, v49, v50
	v_max3_f32 v214, v56, v57, v58
	v_max3_f32 v175, v175, v51, v52
	v_max3_f32 v214, v214, v59, v60
	v_max3_f32 v175, v175, v53, v54
	v_max3_f32 v214, v214, v61, v62
	v_max3_f32 v175, v175, v55, v63
	v_max_f32_e32 v175, v175, v214
	v_cmp_gt_f32_e32 vcc, v0, v219
	s_cmp_eq_u64 vcc, 0
	s_cbranch_scc1 .Lnsw1el0_keep0
	s_nop 0
	ds_bpermute_b32 v216, v119, v0
	s_waitcnt lgkmcnt(0)
	v_max_f32_e32 v0, v0, v216
	v_max_f32_e32 v173, v168, v0
	v_sub_f32_e32 v0, v168, v173
	v_exp_f32_e32 v0, v0
	v_mov_b32_e32 v168, v173
	v_add_f32_e32 v219, 0x41200000, v173
	v_mul_f32_e32 v169, v169, v0
	v_pk_mul_f32 v[46:47], v[46:47], v[0:1] op_sel_hi:[1,0]
	v_pk_mul_f32 v[44:45], v[44:45], v[0:1] op_sel_hi:[1,0]
	v_pk_mul_f32 v[42:43], v[42:43], v[0:1] op_sel_hi:[1,0]
	v_pk_mul_f32 v[40:41], v[40:41], v[0:1] op_sel_hi:[1,0]
	v_pk_mul_f32 v[38:39], v[38:39], v[0:1] op_sel_hi:[1,0]
	v_pk_mul_f32 v[36:37], v[36:37], v[0:1] op_sel_hi:[1,0]
	v_pk_mul_f32 v[34:35], v[34:35], v[0:1] op_sel_hi:[1,0]
	v_pk_mul_f32 v[32:33], v[32:33], v[0:1] op_sel_hi:[1,0]
	v_pk_mul_f32 v[30:31], v[30:31], v[0:1] op_sel_hi:[1,0]
	v_pk_mul_f32 v[28:29], v[28:29], v[0:1] op_sel_hi:[1,0]
	v_pk_mul_f32 v[26:27], v[26:27], v[0:1] op_sel_hi:[1,0]
	v_pk_mul_f32 v[24:25], v[24:25], v[0:1] op_sel_hi:[1,0]
	v_pk_mul_f32 v[22:23], v[22:23], v[0:1] op_sel_hi:[1,0]
	v_pk_mul_f32 v[20:21], v[20:21], v[0:1] op_sel_hi:[1,0]
	v_pk_mul_f32 v[18:19], v[18:19], v[0:1] op_sel_hi:[1,0]
	v_pk_mul_f32 v[16:17], v[16:17], v[0:1] op_sel_hi:[1,0]

.Lnsw1_elo1:
	v_and_b32_e32 v173, 31, v133
	v_bfe_u32 v213, v133, 5, 1
	v_lshlrev_b32_e32 v213, 3, v213
	v_sub_u32_e32 v173, v173, v213
	s_sub_i32 s4, s8, s6
	s_addk_i32 s4, 0xfe00
	v_add_u32_e32 v173, s4, v173
	v_add_u32_e32 v213, 0xffffffe0, v173
	v_mov_b32_e32 v174, 0xff800000
	v_mad_u32_u24 v0, v218, s37, v14
	v_lshl_add_u32 v215, v159, 1, v14
	ds_read_b128 v[236:239], v0 offset:4608
	ds_read_b128 v[240:243], v0 offset:4640
	ds_read_b128 v[244:247], v0 offset:4672
	ds_read_b128 v[248:251], v0 offset:4704
	s_waitcnt lgkmcnt(3)
	v_mfma_f32_32x32x16_bf16 v[48:63], v[236:239], v[96:99], 0
	s_waitcnt lgkmcnt(2)
	v_mfma_f32_32x32x16_bf16 v[48:63], v[240:243], v[100:103], v[48:63]
	s_waitcnt lgkmcnt(1)
	v_mfma_f32_32x32x16_bf16 v[48:63], v[244:247], v[104:107], v[48:63]
	s_waitcnt lgkmcnt(0)
	v_mfma_f32_32x32x16_bf16 v[48:63], v[248:251], v[108:111], v[48:63]
	ds_read_b128 v[220:223], v215 offset:9280
	ds_read_b128 v[224:227], v215 offset:13888
	ds_read_b128 v[228:231], v215 offset:9312
	ds_read_b128 v[232:235], v215 offset:13920
	s_nop 7
	s_nop 3
	v_cmp_gt_i32_e64 vcc, 0, v213
	v_cmp_gt_i32_e64 s[4:5], 1, v213
	v_cmp_gt_i32_e64 s[6:7], 2, v213
	v_cndmask_b32_e32 v48, v174, v48, vcc
	v_cmp_gt_i32_e64 vcc, 3, v213
	v_cndmask_b32_e64 v49, v174, v49, s[4:5]
	v_cmp_gt_i32_e64 s[4:5], 4, v213
	v_cndmask_b32_e64 v50, v174, v50, s[6:7]
	v_cmp_gt_i32_e64 s[6:7], 5, v213
	v_cndmask_b32_e32 v51, v174, v51, vcc
	v_cmp_gt_i32_e64 vcc, 6, v213
	v_cndmask_b32_e64 v52, v174, v52, s[4:5]
	v_cmp_gt_i32_e64 s[4:5], 7, v213
	v_cndmask_b32_e64 v53, v174, v53, s[6:7]
	v_cmp_gt_i32_e64 s[6:7], 16, v213
	v_cndmask_b32_e32 v54, v174, v54, vcc
	v_cmp_gt_i32_e64 vcc, 17, v213
	v_cndmask_b32_e64 v55, v174, v55, s[4:5]
	v_cmp_gt_i32_e64 s[4:5], 18, v213
	v_cndmask_b32_e64 v56, v174, v56, s[6:7]
	v_cmp_gt_i32_e64 s[6:7], 19, v213
	v_cndmask_b32_e32 v57, v174, v57, vcc
	v_cmp_gt_i32_e64 vcc, 20, v213
	v_cndmask_b32_e64 v58, v174, v58, s[4:5]
	v_cmp_gt_i32_e64 s[4:5], 21, v213
	v_cndmask_b32_e64 v59, v174, v59, s[6:7]
	v_cmp_gt_i32_e64 s[6:7], 22, v213
	v_cndmask_b32_e32 v60, v174, v60, vcc
	v_cmp_gt_i32_e64 vcc, 23, v213
	v_cndmask_b32_e64 v61, v174, v61, s[4:5]
	s_nop 0
	v_cndmask_b32_e64 v62, v174, v62, s[6:7]
	s_nop 0
	v_cndmask_b32_e32 v63, v174, v63, vcc
	s_nop 0
	v_max3_f32 v175, v48, v49, v50
	v_max3_f32 v214, v56, v57, v58
	v_max3_f32 v175, v175, v51, v52
	v_max3_f32 v214, v214, v59, v60
	v_max3_f32 v175, v175, v53, v54
	v_max3_f32 v214, v214, v61, v62
	v_max3_f32 v175, v175, v55, v63
	v_max_f32_e32 v175, v175, v214
	v_cmp_gt_f32_e32 vcc, v175, v219
	s_cmp_eq_u64 vcc, 0
	s_cbranch_scc1 .Lnsw1el1_keep1
	s_nop 0
	ds_bpermute_b32 v214, v119, v175
	s_waitcnt lgkmcnt(0)
	v_max_f32_e32 v175, v175, v214
	v_max_f32_e32 v173, v168, v175
	v_sub_f32_e32 v0, v168, v173
	v_exp_f32_e32 v0, v0
	v_mov_b32_e32 v168, v173
	v_add_f32_e32 v219, 0x41200000, v173
	v_mul_f32_e32 v169, v169, v0
	v_pk_mul_f32 v[46:47], v[46:47], v[0:1] op_sel_hi:[1,0]
	v_pk_mul_f32 v[44:45], v[44:45], v[0:1] op_sel_hi:[1,0]
	v_pk_mul_f32 v[42:43], v[42:43], v[0:1] op_sel_hi:[1,0]
	v_pk_mul_f32 v[40:41], v[40:41], v[0:1] op_sel_hi:[1,0]
	v_pk_mul_f32 v[38:39], v[38:39], v[0:1] op_sel_hi:[1,0]
	v_pk_mul_f32 v[36:37], v[36:37], v[0:1] op_sel_hi:[1,0]
	v_pk_mul_f32 v[34:35], v[34:35], v[0:1] op_sel_hi:[1,0]
	v_pk_mul_f32 v[32:33], v[32:33], v[0:1] op_sel_hi:[1,0]
	v_pk_mul_f32 v[30:31], v[30:31], v[0:1] op_sel_hi:[1,0]
	v_pk_mul_f32 v[28:29], v[28:29], v[0:1] op_sel_hi:[1,0]
	v_pk_mul_f32 v[26:27], v[26:27], v[0:1] op_sel_hi:[1,0]
	v_pk_mul_f32 v[24:25], v[24:25], v[0:1] op_sel_hi:[1,0]
	v_pk_mul_f32 v[22:23], v[22:23], v[0:1] op_sel_hi:[1,0]
	v_pk_mul_f32 v[20:21], v[20:21], v[0:1] op_sel_hi:[1,0]
	v_pk_mul_f32 v[18:19], v[18:19], v[0:1] op_sel_hi:[1,0]
	v_pk_mul_f32 v[16:17], v[16:17], v[0:1] op_sel_hi:[1,0]
